# rowwise reductions: xor-8/2/1 butterfly steps through DPP (row_ror, quad_perm) instead of ds_bpermute round trips
# baseline (speedup 1.0000x reference)
; DI float lo2f(unsigned v) { return __uint_as_float(v << 16); }
; DI float hi2f(unsigned v) { return __uint_as_float(v & 0xffff0000u); }
; DI float wave_sum(float v) { for (int o = 32; o > 0; o >>= 1) v += __shfl_xor(v, o); return v; }
; DI void phase_rowwise(PP p, bool first, const u16* src, const float* g_post, int l_res, int gate_idx,
;                       bool write_h, const float* g_pre, int l_mod, int shift_idx, int scale_idx, bool skip_ctx) {
;     ...
;     if (src) {
;       float y[16]; float ss = 0.f;
; #pragma unroll
;       for (int i = 0; i < 4; ++i) { U2 v = *(const U2*)(src + (size_t)r * DM + i * 256 + lane * 4);
;         y[4 * i] = lo2f(v.x); y[4 * i + 1] = hi2f(v.x); y[4 * i + 2] = lo2f(v.y); y[4 * i + 3] = hi2f(v.y); }
; #pragma unroll
;       for (int i = 0; i < 16; ++i) ss += y[i] * y[i];
;       ss = wave_sum(ss);
;       float rstd = rsqrtf(ss * (1.f / DM) + EPS);
.Lrw20_nxt_go:
	s_lshl_b32 s7, s2, 8
	s_add_i32 s7, s7, s3
	s_lshl_b32 s12, s2, 13
	s_add_i32 s12, s12, s3
	s_add_i32 s12, s12, 0xffffff00
	s_cmp_eq_u32 s6, 1
	s_cselect_b32 s7, s7, s12
	s_cselect_b32 s9, 4, s2
	s_cselect_b64 s[12:13], -1, 0
	s_lshl_b32 s7, s7, 12
	v_add_u32_e32 v74, s7, v2
	v_cndmask_b32_e64 v0, v234, v236, s[12:13]
	v_cndmask_b32_e64 v227, v235, v237, s[12:13]
	v_mov_b32_e32 v190, v0
	v_mov_b32_e32 v191, v227
	v_lshl_add_u64 v[190:191], v[190:191], 0, v[74:75]
	v_cndmask_b32_e64 v192, v230, v232, s[12:13]
	v_cndmask_b32_e64 v193, v231, v233, s[12:13]
	v_lshl_add_u64 v[192:193], v[192:193], 0, v[74:75]
	s_lshl_b32 s7, s1, 11
	v_mov_b32_e32 v74, s7
	v_lshl_add_u64 v[196:197], v[180:181], 0, v[74:75]
	global_load_dwordx4 v[26:29], v[190:191], off
	global_load_dwordx4 v[30:33], v[190:191], off offset:1024
	global_load_dwordx4 v[34:37], v[190:191], off offset:2048
	global_load_dwordx4 v[38:41], v[190:191], off offset:3072
	global_load_dwordx2 v[42:43], v[196:197], off
	global_load_dwordx2 v[44:45], v[196:197], off offset:512
	global_load_dwordx2 v[46:47], v[196:197], off offset:1024
	global_load_dwordx2 v[48:49], v[196:197], off offset:1536
	v_lshlrev_b32_e32 v58, 16, v50
	v_and_b32_e32 v59, 0xffff0000, v50
	v_lshlrev_b32_e32 v60, 16, v51
	v_and_b32_e32 v61, 0xffff0000, v51
	v_lshlrev_b32_e32 v62, 16, v52
	v_and_b32_e32 v63, 0xffff0000, v52
	v_lshlrev_b32_e32 v64, 16, v53
	v_and_b32_e32 v65, 0xffff0000, v53
	v_lshlrev_b32_e32 v66, 16, v54
	v_and_b32_e32 v67, 0xffff0000, v54
	v_lshlrev_b32_e32 v68, 16, v55
	v_and_b32_e32 v69, 0xffff0000, v55
	v_lshlrev_b32_e32 v70, 16, v56
	v_and_b32_e32 v71, 0xffff0000, v56
	v_lshlrev_b32_e32 v72, 16, v57
	v_and_b32_e32 v73, 0xffff0000, v57
	v_mul_f32_e32 v226, v58, v58
	v_mul_f32_e32 v227, v59, v59
	v_add_f32_e32 v226, v226, v227
	v_mul_f32_e32 v227, v60, v60
	v_add_f32_e32 v226, v227, v226
	v_mul_f32_e32 v227, v61, v61
	v_add_f32_e32 v226, v227, v226
	v_mul_f32_e32 v227, v62, v62
	v_add_f32_e32 v226, v227, v226
	v_mul_f32_e32 v227, v63, v63
	v_add_f32_e32 v226, v227, v226
	v_mul_f32_e32 v227, v64, v64
	v_add_f32_e32 v226, v227, v226
	v_mul_f32_e32 v227, v65, v65
	v_add_f32_e32 v226, v227, v226
	v_mul_f32_e32 v227, v66, v66
	v_add_f32_e32 v226, v227, v226
	v_mul_f32_e32 v227, v67, v67
	v_add_f32_e32 v226, v227, v226
	v_mul_f32_e32 v227, v68, v68
	v_add_f32_e32 v226, v227, v226
	v_mul_f32_e32 v227, v69, v69
	v_add_f32_e32 v226, v227, v226
	v_mul_f32_e32 v227, v70, v70
	v_add_f32_e32 v226, v227, v226
	v_mul_f32_e32 v227, v71, v71
	v_add_f32_e32 v226, v227, v226
	v_mul_f32_e32 v227, v72, v72
	v_add_f32_e32 v226, v227, v226
	v_mul_f32_e32 v227, v73, v73
	v_add_f32_e32 v226, v227, v226
	ds_bpermute_b32 v227, v4, v226
	s_waitcnt lgkmcnt(0)
	v_add_f32_e32 v226, v226, v227
	ds_bpermute_b32 v227, v5, v226
	s_waitcnt lgkmcnt(0)
	v_add_f32_e32 v226, v226, v227
	s_nop 1
	v_add_f32_dpp v226, v226, v226 row_ror:8 row_mask:0xf bank_mask:0xf
	ds_bpermute_b32 v227, v7, v226
	s_waitcnt lgkmcnt(0)
	v_add_f32_e32 v226, v226, v227
	s_nop 1
	v_add_f32_dpp v226, v226, v226 quad_perm:[2,3,0,1] row_mask:0xf bank_mask:0xf
	s_nop 1
	v_add_f32_dpp v226, v226, v226 quad_perm:[1,0,3,2] row_mask:0xf bank_mask:0xf
	v_fmamk_f32 v226, v226, 0x3a800000, v162
	s_mov_b32 s7, 0x800000
	v_cmp_gt_f32_e32 vcc, s7, v226
	v_mul_f32_e32 v227, 0x4b800000, v226
	s_nop 0
	v_cndmask_b32_e32 v226, v226, v227, vcc
	v_rsq_f32_e32 v226, v226
	s_nop 0
	v_mul_f32_e32 v227, 0x45800000, v226
	v_cndmask_b32_e32 v228, v226, v227, vcc
	s_waitcnt vmcnt(8)
	v_pk_mul_f32 v[58:59], v[228:229], v[58:59] op_sel_hi:[0,1]
	v_pk_mul_f32 v[58:59], v[58:59], v[118:119]
	v_pk_fma_f32 v[10:11], v[134:135], v[58:59], v[10:11]
	v_pk_mul_f32 v[60:61], v[228:229], v[60:61] op_sel_hi:[0,1]
	v_pk_mul_f32 v[60:61], v[60:61], v[120:121]
	v_pk_fma_f32 v[12:13], v[136:137], v[60:61], v[12:13]
	v_pk_mul_f32 v[62:63], v[228:229], v[62:63] op_sel_hi:[0,1]
	v_pk_mul_f32 v[62:63], v[62:63], v[122:123]
	v_pk_fma_f32 v[14:15], v[138:139], v[62:63], v[14:15]
	v_pk_mul_f32 v[64:65], v[228:229], v[64:65] op_sel_hi:[0,1]
	v_pk_mul_f32 v[64:65], v[64:65], v[124:125]
	v_pk_fma_f32 v[16:17], v[140:141], v[64:65], v[16:17]
	v_pk_mul_f32 v[66:67], v[228:229], v[66:67] op_sel_hi:[0,1]
	v_pk_mul_f32 v[66:67], v[66:67], v[126:127]
	v_pk_fma_f32 v[18:19], v[142:143], v[66:67], v[18:19]
	v_pk_mul_f32 v[68:69], v[228:229], v[68:69] op_sel_hi:[0,1]
	v_pk_mul_f32 v[68:69], v[68:69], v[128:129]
	v_pk_fma_f32 v[20:21], v[144:145], v[68:69], v[20:21]
	v_pk_mul_f32 v[70:71], v[228:229], v[70:71] op_sel_hi:[0,1]
	v_pk_mul_f32 v[70:71], v[70:71], v[130:131]
	v_pk_fma_f32 v[22:23], v[146:147], v[70:71], v[22:23]
	v_pk_mul_f32 v[72:73], v[228:229], v[72:73] op_sel_hi:[0,1]
	v_pk_mul_f32 v[72:73], v[72:73], v[132:133]
	v_pk_fma_f32 v[24:25], v[148:149], v[72:73], v[24:25]
	s_cmp_eq_u32 s10, 1
	s_cbranch_scc1 .Lrw20_noh_st
; DI unsigned pack2(float a, float b) { F2 v = {a, b}; B2 r = __builtin_convertvector(v, B2); return __builtin_bit_cast(unsigned, r); }
; DI float wave_sum(float v) { for (int o = 32; o > 0; o >>= 1) v += __shfl_xor(v, o); return v; }
; DI const float* modvec(PP p, int l, int s, int idx) { return (const float*)(p->ws + S_MOD) + ((size_t)(l * 5 + s) * 6 + idx) * DM; }
; DI void phase_rowwise(PP p, bool first, const u16* src, const float* g_post, int l_res, int gate_idx,
;                       bool write_h, const float* g_pre, int l_mod, int shift_idx, int scale_idx, bool skip_ctx) {
;     ...
;     if (write_h) {
;       float ss = 0.f;
; #pragma unroll
;       for (int i = 0; i < 16; ++i) ss += x[i] * x[i];
;       ss = wave_sum(ss);
;       float rstd = rsqrtf(ss * (1.f / DM) + EPS);
;       const float* sh = modvec(p, l_mod, s, shift_idx); const float* sc = modvec(p, l_mod, s, scale_idx);
; #pragma unroll
;       for (int i = 0; i < 4; ++i) {
;         int k = i * 256 + lane * 4;
;         F4 g = *(const F4*)(g_pre + k); F4 a = *(const F4*)(sh + k); F4 c = *(const F4*)(sc + k);
;         float h0 = x[4 * i] * rstd * g.x * (1.f + c.x) + a.x, h1 = x[4 * i + 1] * rstd * g.y * (1.f + c.y) + a.y;
;         float h2 = x[4 * i + 2] * rstd * g.z * (1.f + c.z) + a.z, h3 = x[4 * i + 3] * rstd * g.w * (1.f + c.w) + a.w;
;         *(U2*)(H + (size_t)r * DM + k) = mku2(pack2(h0, h1), pack2(h2, h3));
;       }
;     }
	global_load_dwordx4 v[118:121], v[172:173], off
	global_load_dwordx4 v[122:125], v[172:173], off offset:1024
	global_load_dwordx4 v[126:129], v[172:173], off offset:2048
	global_load_dwordx4 v[130:133], v[172:173], off offset:3072
	global_load_dwordx4 v[134:137], v[222:223], off
	global_load_dwordx4 v[138:141], v[222:223], off offset:1024
	global_load_dwordx4 v[142:145], v[222:223], off offset:2048
	global_load_dwordx4 v[146:149], v[222:223], off offset:3072
	global_load_dwordx4 v[150:153], v[224:225], off
	global_load_dwordx4 v[154:157], v[224:225], off offset:1024
	global_load_dwordx4 v[158:161], v[224:225], off offset:2048
	global_load_dwordx4 v[166:169], v[224:225], off offset:3072
	global_store_dwordx4 v[188:189], v[10:13], off
	global_store_dwordx4 v[188:189], v[14:17], off offset:1024
	global_store_dwordx4 v[188:189], v[18:21], off offset:2048
	global_store_dwordx4 v[188:189], v[22:25], off offset:3072
	v_mul_f32_e32 v226, v10, v10
	v_mul_f32_e32 v227, v11, v11
	v_add_f32_e32 v226, v226, v227
	v_mul_f32_e32 v227, v12, v12
	v_add_f32_e32 v226, v227, v226
	v_mul_f32_e32 v227, v13, v13
	v_add_f32_e32 v226, v227, v226
	v_mul_f32_e32 v227, v14, v14
	v_add_f32_e32 v226, v227, v226
	v_mul_f32_e32 v227, v15, v15
	v_add_f32_e32 v226, v227, v226
	v_mul_f32_e32 v227, v16, v16
	v_add_f32_e32 v226, v227, v226
	v_mul_f32_e32 v227, v17, v17
	v_add_f32_e32 v226, v227, v226
	v_mul_f32_e32 v227, v18, v18
	v_add_f32_e32 v226, v227, v226
	v_mul_f32_e32 v227, v19, v19
	v_add_f32_e32 v226, v227, v226
	v_mul_f32_e32 v227, v20, v20
	v_add_f32_e32 v226, v227, v226
	v_mul_f32_e32 v227, v21, v21
	v_add_f32_e32 v226, v227, v226
	v_mul_f32_e32 v227, v22, v22
	v_add_f32_e32 v226, v227, v226
	v_mul_f32_e32 v227, v23, v23
	v_add_f32_e32 v226, v227, v226
	v_mul_f32_e32 v227, v24, v24
	v_add_f32_e32 v226, v227, v226
	v_mul_f32_e32 v227, v25, v25
	v_add_f32_e32 v226, v227, v226
	ds_bpermute_b32 v227, v4, v226
	s_waitcnt lgkmcnt(0)
	v_add_f32_e32 v226, v226, v227
	ds_bpermute_b32 v227, v5, v226
	s_waitcnt lgkmcnt(0)
	v_add_f32_e32 v226, v226, v227
	s_nop 1
	v_add_f32_dpp v226, v226, v226 row_ror:8 row_mask:0xf bank_mask:0xf
	ds_bpermute_b32 v227, v7, v226
	s_waitcnt lgkmcnt(0)
	v_add_f32_e32 v226, v226, v227
	s_nop 1
	v_add_f32_dpp v226, v226, v226 quad_perm:[2,3,0,1] row_mask:0xf bank_mask:0xf
	s_nop 1
	v_add_f32_dpp v226, v226, v226 quad_perm:[1,0,3,2] row_mask:0xf bank_mask:0xf
	v_fmamk_f32 v226, v226, 0x3a800000, v162
	s_mov_b32 s7, 0x800000
	v_cmp_gt_f32_e32 vcc, s7, v226
	v_mul_f32_e32 v227, 0x4b800000, v226
	s_nop 0
	v_cndmask_b32_e32 v226, v226, v227, vcc
	v_rsq_f32_e32 v226, v226
	s_nop 0
	v_mul_f32_e32 v227, 0x45800000, v226
	v_cndmask_b32_e32 v228, v226, v227, vcc
	s_waitcnt vmcnt(4)
	v_pk_mul_f32 v[10:11], v[10:11], v[228:229] op_sel_hi:[1,0]
	v_pk_mul_f32 v[10:11], v[118:119], v[10:11]
	v_pk_add_f32 v[58:59], v[150:151], 1.0 op_sel_hi:[1,0]
	s_nop 0
	v_pk_fma_f32 v[10:11], v[58:59], v[10:11], v[134:135]
	v_pk_mul_f32 v[12:13], v[12:13], v[228:229] op_sel_hi:[1,0]
	v_pk_mul_f32 v[12:13], v[120:121], v[12:13]
	v_pk_add_f32 v[60:61], v[152:153], 1.0 op_sel_hi:[1,0]
	s_nop 0
	v_pk_fma_f32 v[12:13], v[60:61], v[12:13], v[136:137]
	v_cvt_pk_bf16_f32 v66, v10, v11
	v_cvt_pk_bf16_f32 v67, v12, v13
	global_store_dwordx2 v[218:219], v[66:67], off
	s_nop 1
	v_pk_mul_f32 v[14:15], v[14:15], v[228:229] op_sel_hi:[1,0]
	v_pk_mul_f32 v[14:15], v[122:123], v[14:15]
	v_pk_add_f32 v[58:59], v[154:155], 1.0 op_sel_hi:[1,0]
	s_nop 0
	v_pk_fma_f32 v[14:15], v[58:59], v[14:15], v[138:139]
	v_pk_mul_f32 v[16:17], v[16:17], v[228:229] op_sel_hi:[1,0]
	v_pk_mul_f32 v[16:17], v[124:125], v[16:17]
	v_pk_add_f32 v[60:61], v[156:157], 1.0 op_sel_hi:[1,0]
	s_nop 0
	v_pk_fma_f32 v[16:17], v[60:61], v[16:17], v[140:141]
	v_cvt_pk_bf16_f32 v66, v14, v15
	v_cvt_pk_bf16_f32 v67, v16, v17
	global_store_dwordx2 v[218:219], v[66:67], off offset:512
	s_nop 1
	v_pk_mul_f32 v[18:19], v[18:19], v[228:229] op_sel_hi:[1,0]
	v_pk_mul_f32 v[18:19], v[126:127], v[18:19]
	v_pk_add_f32 v[58:59], v[158:159], 1.0 op_sel_hi:[1,0]
	s_nop 0
	v_pk_fma_f32 v[18:19], v[58:59], v[18:19], v[142:143]
	v_pk_mul_f32 v[20:21], v[20:21], v[228:229] op_sel_hi:[1,0]
	v_pk_mul_f32 v[20:21], v[128:129], v[20:21]
	v_pk_add_f32 v[60:61], v[160:161], 1.0 op_sel_hi:[1,0]
	s_nop 0
	v_pk_fma_f32 v[20:21], v[60:61], v[20:21], v[144:145]
	v_cvt_pk_bf16_f32 v66, v18, v19
	v_cvt_pk_bf16_f32 v67, v20, v21
	global_store_dwordx2 v[218:219], v[66:67], off offset:1024
	s_nop 1
	v_pk_mul_f32 v[22:23], v[22:23], v[228:229] op_sel_hi:[1,0]
	v_pk_mul_f32 v[22:23], v[130:131], v[22:23]
	v_pk_add_f32 v[58:59], v[166:167], 1.0 op_sel_hi:[1,0]
	s_nop 0
	v_pk_fma_f32 v[22:23], v[58:59], v[22:23], v[146:147]
	v_pk_mul_f32 v[24:25], v[24:25], v[228:229] op_sel_hi:[1,0]
	v_pk_mul_f32 v[24:25], v[132:133], v[24:25]
	v_pk_add_f32 v[60:61], v[168:169], 1.0 op_sel_hi:[1,0]
	s_nop 0
	v_pk_fma_f32 v[24:25], v[60:61], v[24:25], v[148:149]
	v_cvt_pk_bf16_f32 v66, v22, v23
	v_cvt_pk_bf16_f32 v67, v24, v25
	global_store_dwordx2 v[218:219], v[66:67], off offset:1536
	s_nop 1
	s_branch .Lrw20_noh

; DI float lo2f(unsigned v) { return __uint_as_float(v << 16); }
; DI float hi2f(unsigned v) { return __uint_as_float(v & 0xffff0000u); }
; DI float wave_sum(float v) { for (int o = 32; o > 0; o >>= 1) v += __shfl_xor(v, o); return v; }
; DI void phase_rowwise(PP p, bool first, const u16* src, const float* g_post, int l_res, int gate_idx,
;                       bool write_h, const float* g_pre, int l_mod, int shift_idx, int scale_idx, bool skip_ctx) {
;     ...
;     if (src) {
;       float y[16]; float ss = 0.f;
; #pragma unroll
;       for (int i = 0; i < 4; ++i) { U2 v = *(const U2*)(src + (size_t)r * DM + i * 256 + lane * 4);
;         y[4 * i] = lo2f(v.x); y[4 * i + 1] = hi2f(v.x); y[4 * i + 2] = lo2f(v.y); y[4 * i + 3] = hi2f(v.y); }
; #pragma unroll
;       for (int i = 0; i < 16; ++i) ss += y[i] * y[i];
;       ss = wave_sum(ss);
;       float rstd = rsqrtf(ss * (1.f / DM) + EPS);
.Lrw17_nxt_go:
	s_lshl_b32 s7, s2, 8
	s_add_i32 s7, s7, s3
	s_lshl_b32 s12, s2, 13
	s_add_i32 s12, s12, s3
	s_add_i32 s12, s12, 0xffffff00
	s_cmp_eq_u32 s6, 1
	s_cselect_b32 s7, s7, s12
	s_cselect_b32 s9, 4, s2
	s_cselect_b64 s[12:13], -1, 0
	s_lshl_b32 s7, s7, 12
	v_add_u32_e32 v74, s7, v2
	v_cndmask_b32_e64 v0, v234, v236, s[12:13]
	v_cndmask_b32_e64 v227, v235, v237, s[12:13]
	v_mov_b32_e32 v190, v0
	v_mov_b32_e32 v191, v227
	v_lshl_add_u64 v[190:191], v[190:191], 0, v[74:75]
	v_cndmask_b32_e64 v192, v230, v232, s[12:13]
	v_cndmask_b32_e64 v193, v231, v233, s[12:13]
	v_lshl_add_u64 v[192:193], v[192:193], 0, v[74:75]
	s_lshl_b32 s7, s1, 11
	v_mov_b32_e32 v74, s7
	v_lshl_add_u64 v[196:197], v[180:181], 0, v[74:75]
	global_load_dwordx4 v[26:29], v[190:191], off
	global_load_dwordx4 v[30:33], v[190:191], off offset:1024
	global_load_dwordx4 v[34:37], v[190:191], off offset:2048
	global_load_dwordx4 v[38:41], v[190:191], off offset:3072
	global_load_dwordx2 v[42:43], v[196:197], off
	global_load_dwordx2 v[44:45], v[196:197], off offset:512
	global_load_dwordx2 v[46:47], v[196:197], off offset:1024
	global_load_dwordx2 v[48:49], v[196:197], off offset:1536
	v_lshlrev_b32_e32 v58, 16, v50
	v_and_b32_e32 v59, 0xffff0000, v50
	v_lshlrev_b32_e32 v60, 16, v51
	v_and_b32_e32 v61, 0xffff0000, v51
	v_lshlrev_b32_e32 v62, 16, v52
	v_and_b32_e32 v63, 0xffff0000, v52
	v_lshlrev_b32_e32 v64, 16, v53
	v_and_b32_e32 v65, 0xffff0000, v53
	v_lshlrev_b32_e32 v66, 16, v54
	v_and_b32_e32 v67, 0xffff0000, v54
	v_lshlrev_b32_e32 v68, 16, v55
	v_and_b32_e32 v69, 0xffff0000, v55
	v_lshlrev_b32_e32 v70, 16, v56
	v_and_b32_e32 v71, 0xffff0000, v56
	v_lshlrev_b32_e32 v72, 16, v57
	v_and_b32_e32 v73, 0xffff0000, v57
	v_mul_f32_e32 v226, v58, v58
	v_mul_f32_e32 v227, v59, v59
	v_add_f32_e32 v226, v226, v227
	v_mul_f32_e32 v227, v60, v60
	v_add_f32_e32 v226, v227, v226
	v_mul_f32_e32 v227, v61, v61
	v_add_f32_e32 v226, v227, v226
	v_mul_f32_e32 v227, v62, v62
	v_add_f32_e32 v226, v227, v226
	v_mul_f32_e32 v227, v63, v63
	v_add_f32_e32 v226, v227, v226
	v_mul_f32_e32 v227, v64, v64
	v_add_f32_e32 v226, v227, v226
	v_mul_f32_e32 v227, v65, v65
	v_add_f32_e32 v226, v227, v226
	v_mul_f32_e32 v227, v66, v66
	v_add_f32_e32 v226, v227, v226
	v_mul_f32_e32 v227, v67, v67
	v_add_f32_e32 v226, v227, v226
	v_mul_f32_e32 v227, v68, v68
	v_add_f32_e32 v226, v227, v226
	v_mul_f32_e32 v227, v69, v69
	v_add_f32_e32 v226, v227, v226
	v_mul_f32_e32 v227, v70, v70
	v_add_f32_e32 v226, v227, v226
	v_mul_f32_e32 v227, v71, v71
	v_add_f32_e32 v226, v227, v226
	v_mul_f32_e32 v227, v72, v72
	v_add_f32_e32 v226, v227, v226
	v_mul_f32_e32 v227, v73, v73
	v_add_f32_e32 v226, v227, v226
	ds_bpermute_b32 v227, v4, v226
	s_waitcnt lgkmcnt(0)
	v_add_f32_e32 v226, v226, v227
	ds_bpermute_b32 v227, v5, v226
	s_waitcnt lgkmcnt(0)
	v_add_f32_e32 v226, v226, v227
	s_nop 1
	v_add_f32_dpp v226, v226, v226 row_ror:8 row_mask:0xf bank_mask:0xf
	ds_bpermute_b32 v227, v7, v226
	s_waitcnt lgkmcnt(0)
	v_add_f32_e32 v226, v226, v227
	s_nop 1
	v_add_f32_dpp v226, v226, v226 quad_perm:[2,3,0,1] row_mask:0xf bank_mask:0xf
	s_nop 1
	v_add_f32_dpp v226, v226, v226 quad_perm:[1,0,3,2] row_mask:0xf bank_mask:0xf
	v_fmamk_f32 v226, v226, 0x3a800000, v162
	s_mov_b32 s7, 0x800000
	v_cmp_gt_f32_e32 vcc, s7, v226
	v_mul_f32_e32 v227, 0x4b800000, v226
	s_nop 0
	v_cndmask_b32_e32 v226, v226, v227, vcc
	v_rsq_f32_e32 v226, v226
	s_nop 0
	v_mul_f32_e32 v227, 0x45800000, v226
	v_cndmask_b32_e32 v228, v226, v227, vcc
	s_waitcnt vmcnt(8)
; DI unsigned pack2(float a, float b) { F2 v = {a, b}; B2 r = __builtin_convertvector(v, B2); return __builtin_bit_cast(unsigned, r); }
; DI float wave_sum(float v) { for (int o = 32; o > 0; o >>= 1) v += __shfl_xor(v, o); return v; }
; DI const float* modvec(PP p, int l, int s, int idx) { return (const float*)(p->ws + S_MOD) + ((size_t)(l * 5 + s) * 6 + idx) * DM; }
; DI void phase_rowwise(PP p, bool first, const u16* src, const float* g_post, int l_res, int gate_idx,
;                       bool write_h, const float* g_pre, int l_mod, int shift_idx, int scale_idx, bool skip_ctx) {
;     ...
; #pragma unroll
;       for (int i = 0; i < 4; ++i) {
;         int k = i * 256 + lane * 4;
;         F4 g = *(const F4*)(g_post + k); F4 gt = *(const F4*)(gate + k);
;         x[4 * i] += gt.x * (y[4 * i] * rstd * g.x); x[4 * i + 1] += gt.y * (y[4 * i + 1] * rstd * g.y);
;         x[4 * i + 2] += gt.z * (y[4 * i + 2] * rstd * g.z); x[4 * i + 3] += gt.w * (y[4 * i + 3] * rstd * g.w);
;         *(F4*)(xo + k) = mkf4(x[4 * i], x[4 * i + 1], x[4 * i + 2], x[4 * i + 3]);
;       }
;     }
;     if (write_h) {
;       float ss = 0.f;
; #pragma unroll
;       for (int i = 0; i < 16; ++i) ss += x[i] * x[i];
;       ss = wave_sum(ss);
;       float rstd = rsqrtf(ss * (1.f / DM) + EPS);
;       const float* sh = modvec(p, l_mod, s, shift_idx); const float* sc = modvec(p, l_mod, s, scale_idx);
; #pragma unroll
;       for (int i = 0; i < 4; ++i) {
;         int k = i * 256 + lane * 4;
;         F4 g = *(const F4*)(g_pre + k); F4 a = *(const F4*)(sh + k); F4 c = *(const F4*)(sc + k);
;         float h0 = x[4 * i] * rstd * g.x * (1.f + c.x) + a.x, h1 = x[4 * i + 1] * rstd * g.y * (1.f + c.y) + a.y;
;         float h2 = x[4 * i + 2] * rstd * g.z * (1.f + c.z) + a.z, h3 = x[4 * i + 3] * rstd * g.w * (1.f + c.w) + a.w;
;         *(U2*)(H + (size_t)r * DM + k) = mku2(pack2(h0, h1), pack2(h2, h3));
;       }
	v_pk_mul_f32 v[58:59], v[228:229], v[58:59] op_sel_hi:[0,1]
	v_pk_mul_f32 v[58:59], v[58:59], v[118:119]
	v_pk_fma_f32 v[10:11], v[134:135], v[58:59], v[10:11]
	v_pk_mul_f32 v[60:61], v[228:229], v[60:61] op_sel_hi:[0,1]
	v_pk_mul_f32 v[60:61], v[60:61], v[120:121]
	v_pk_fma_f32 v[12:13], v[136:137], v[60:61], v[12:13]
	v_pk_mul_f32 v[62:63], v[228:229], v[62:63] op_sel_hi:[0,1]
	v_pk_mul_f32 v[62:63], v[62:63], v[122:123]
	v_pk_fma_f32 v[14:15], v[138:139], v[62:63], v[14:15]
	v_pk_mul_f32 v[64:65], v[228:229], v[64:65] op_sel_hi:[0,1]
	v_pk_mul_f32 v[64:65], v[64:65], v[124:125]
	v_pk_fma_f32 v[16:17], v[140:141], v[64:65], v[16:17]
	v_pk_mul_f32 v[66:67], v[228:229], v[66:67] op_sel_hi:[0,1]
	v_pk_mul_f32 v[66:67], v[66:67], v[126:127]
	v_pk_fma_f32 v[18:19], v[142:143], v[66:67], v[18:19]
	v_pk_mul_f32 v[68:69], v[228:229], v[68:69] op_sel_hi:[0,1]
	v_pk_mul_f32 v[68:69], v[68:69], v[128:129]
	v_pk_fma_f32 v[20:21], v[144:145], v[68:69], v[20:21]
	v_pk_mul_f32 v[70:71], v[228:229], v[70:71] op_sel_hi:[0,1]
	v_pk_mul_f32 v[70:71], v[70:71], v[130:131]
	v_pk_fma_f32 v[22:23], v[146:147], v[70:71], v[22:23]
	v_pk_mul_f32 v[72:73], v[228:229], v[72:73] op_sel_hi:[0,1]
	v_pk_mul_f32 v[72:73], v[72:73], v[132:133]
	v_pk_fma_f32 v[24:25], v[148:149], v[72:73], v[24:25]
	global_load_dwordx4 v[118:121], v[172:173], off
	global_load_dwordx4 v[122:125], v[172:173], off offset:1024
	global_load_dwordx4 v[126:129], v[172:173], off offset:2048
	global_load_dwordx4 v[130:133], v[172:173], off offset:3072
	global_load_dwordx4 v[134:137], v[222:223], off
	global_load_dwordx4 v[138:141], v[222:223], off offset:1024
	global_load_dwordx4 v[142:145], v[222:223], off offset:2048
	global_load_dwordx4 v[146:149], v[222:223], off offset:3072
	global_load_dwordx4 v[150:153], v[224:225], off
	global_load_dwordx4 v[154:157], v[224:225], off offset:1024
	global_load_dwordx4 v[158:161], v[224:225], off offset:2048
	global_load_dwordx4 v[166:169], v[224:225], off offset:3072
	global_store_dwordx4 v[188:189], v[10:13], off
	global_store_dwordx4 v[188:189], v[14:17], off offset:1024
	global_store_dwordx4 v[188:189], v[18:21], off offset:2048
	global_store_dwordx4 v[188:189], v[22:25], off offset:3072
	v_mul_f32_e32 v226, v10, v10
	v_mul_f32_e32 v227, v11, v11
	v_add_f32_e32 v226, v226, v227
	v_mul_f32_e32 v227, v12, v12
	v_add_f32_e32 v226, v227, v226
	v_mul_f32_e32 v227, v13, v13
	v_add_f32_e32 v226, v227, v226
	v_mul_f32_e32 v227, v14, v14
	v_add_f32_e32 v226, v227, v226
	v_mul_f32_e32 v227, v15, v15
	v_add_f32_e32 v226, v227, v226
	v_mul_f32_e32 v227, v16, v16
	v_add_f32_e32 v226, v227, v226
	v_mul_f32_e32 v227, v17, v17
	v_add_f32_e32 v226, v227, v226
	v_mul_f32_e32 v227, v18, v18
	v_add_f32_e32 v226, v227, v226
	v_mul_f32_e32 v227, v19, v19
	v_add_f32_e32 v226, v227, v226
	v_mul_f32_e32 v227, v20, v20
	v_add_f32_e32 v226, v227, v226
	v_mul_f32_e32 v227, v21, v21
	v_add_f32_e32 v226, v227, v226
	v_mul_f32_e32 v227, v22, v22
	v_add_f32_e32 v226, v227, v226
	v_mul_f32_e32 v227, v23, v23
	v_add_f32_e32 v226, v227, v226
	v_mul_f32_e32 v227, v24, v24
	v_add_f32_e32 v226, v227, v226
	v_mul_f32_e32 v227, v25, v25
	v_add_f32_e32 v226, v227, v226
	ds_bpermute_b32 v227, v4, v226
	s_waitcnt lgkmcnt(0)
	v_add_f32_e32 v226, v226, v227
	ds_bpermute_b32 v227, v5, v226
	s_waitcnt lgkmcnt(0)
	v_add_f32_e32 v226, v226, v227
	s_nop 1
	v_add_f32_dpp v226, v226, v226 row_ror:8 row_mask:0xf bank_mask:0xf
	ds_bpermute_b32 v227, v7, v226
	s_waitcnt lgkmcnt(0)
	v_add_f32_e32 v226, v226, v227
	s_nop 1
	v_add_f32_dpp v226, v226, v226 quad_perm:[2,3,0,1] row_mask:0xf bank_mask:0xf
	s_nop 1
	v_add_f32_dpp v226, v226, v226 quad_perm:[1,0,3,2] row_mask:0xf bank_mask:0xf
	v_fmamk_f32 v226, v226, 0x3a800000, v162
	s_mov_b32 s7, 0x800000
	v_cmp_gt_f32_e32 vcc, s7, v226
	v_mul_f32_e32 v227, 0x4b800000, v226
	s_nop 0
	v_cndmask_b32_e32 v226, v226, v227, vcc
	v_rsq_f32_e32 v226, v226
	s_nop 0
	v_mul_f32_e32 v227, 0x45800000, v226
	v_cndmask_b32_e32 v228, v226, v227, vcc
	s_waitcnt vmcnt(4)
	v_pk_mul_f32 v[10:11], v[10:11], v[228:229] op_sel_hi:[1,0]
	v_pk_mul_f32 v[10:11], v[118:119], v[10:11]
	v_pk_add_f32 v[58:59], v[150:151], 1.0 op_sel_hi:[1,0]
	s_nop 0
	v_pk_fma_f32 v[10:11], v[58:59], v[10:11], v[134:135]
	v_pk_mul_f32 v[12:13], v[12:13], v[228:229] op_sel_hi:[1,0]
	v_pk_mul_f32 v[12:13], v[120:121], v[12:13]
	v_pk_add_f32 v[60:61], v[152:153], 1.0 op_sel_hi:[1,0]
	s_nop 0
	v_pk_fma_f32 v[12:13], v[60:61], v[12:13], v[136:137]
	v_cvt_pk_bf16_f32 v66, v10, v11
	v_cvt_pk_bf16_f32 v67, v12, v13
	global_store_dwordx2 v[218:219], v[66:67], off
	s_nop 1
	v_pk_mul_f32 v[14:15], v[14:15], v[228:229] op_sel_hi:[1,0]
	v_pk_mul_f32 v[14:15], v[122:123], v[14:15]
	v_pk_add_f32 v[58:59], v[154:155], 1.0 op_sel_hi:[1,0]
	s_nop 0
	v_pk_fma_f32 v[14:15], v[58:59], v[14:15], v[138:139]
	v_pk_mul_f32 v[16:17], v[16:17], v[228:229] op_sel_hi:[1,0]
	v_pk_mul_f32 v[16:17], v[124:125], v[16:17]
	v_pk_add_f32 v[60:61], v[156:157], 1.0 op_sel_hi:[1,0]
	s_nop 0
	v_pk_fma_f32 v[16:17], v[60:61], v[16:17], v[140:141]
	v_cvt_pk_bf16_f32 v66, v14, v15
	v_cvt_pk_bf16_f32 v67, v16, v17
	global_store_dwordx2 v[218:219], v[66:67], off offset:512
	s_nop 1
	v_pk_mul_f32 v[18:19], v[18:19], v[228:229] op_sel_hi:[1,0]
	v_pk_mul_f32 v[18:19], v[126:127], v[18:19]
	v_pk_add_f32 v[58:59], v[158:159], 1.0 op_sel_hi:[1,0]
	s_nop 0
	v_pk_fma_f32 v[18:19], v[58:59], v[18:19], v[142:143]
	v_pk_mul_f32 v[20:21], v[20:21], v[228:229] op_sel_hi:[1,0]
	v_pk_mul_f32 v[20:21], v[128:129], v[20:21]
	v_pk_add_f32 v[60:61], v[160:161], 1.0 op_sel_hi:[1,0]
	s_nop 0
	v_pk_fma_f32 v[20:21], v[60:61], v[20:21], v[144:145]
	v_cvt_pk_bf16_f32 v66, v18, v19
	v_cvt_pk_bf16_f32 v67, v20, v21
	global_store_dwordx2 v[218:219], v[66:67], off offset:1024
	s_nop 1
	v_pk_mul_f32 v[22:23], v[22:23], v[228:229] op_sel_hi:[1,0]
	v_pk_mul_f32 v[22:23], v[130:131], v[22:23]
	v_pk_add_f32 v[58:59], v[166:167], 1.0 op_sel_hi:[1,0]
	s_nop 0
	v_pk_fma_f32 v[22:23], v[58:59], v[22:23], v[146:147]
	v_pk_mul_f32 v[24:25], v[24:25], v[228:229] op_sel_hi:[1,0]
	v_pk_mul_f32 v[24:25], v[132:133], v[24:25]
	v_pk_add_f32 v[60:61], v[168:169], 1.0 op_sel_hi:[1,0]
	s_nop 0
	v_pk_fma_f32 v[24:25], v[60:61], v[24:25], v[148:149]
	v_cvt_pk_bf16_f32 v66, v22, v23
	v_cvt_pk_bf16_f32 v67, v24, v25
	global_store_dwordx2 v[218:219], v[66:67], off offset:1536
	s_nop 1
	s_branch .Lrw17_noh

; DI int get_bid() { int t = blockIdx.x; asm volatile("" : "+s"(t)); return t; }
; DI unsigned pack2(float a, float b) { F2 v = {a, b}; B2 r = __builtin_convertvector(v, B2); return __builtin_bit_cast(unsigned, r); }
; DI float wave_sum(float v) { for (int o = 32; o > 0; o >>= 1) v += __shfl_xor(v, o); return v; }
; DI const float* modvec(PP p, int l, int s, int idx) { return (const float*)(p->ws + S_MOD) + ((size_t)(l * 5 + s) * 6 + idx) * DM; }
; DI void phase_rowwise(PP p, bool first, const u16* src, const float* g_post, int l_res, int gate_idx,
;                       bool write_h, const float* g_pre, int l_mod, int shift_idx, int scale_idx, bool skip_ctx) {
;     ...
;   for (int r = get_bid() * 4 + w; r < ROWS; r += gridDim.x * 4) {
;     int b = r / TT, t = r - b * TT;
;     if (skip_ctx && t < CTX) continue;
;     int s = t < CTX ? 4 : b;
;     const float* xin = xrow_in(p, r, first);
;     float x[16];
; #pragma unroll
;     for (int i = 0; i < 4; ++i) { F4 v = *(const F4*)(xin + i * 256 + lane * 4); x[4 * i] = v.x; x[4 * i + 1] = v.y; x[4 * i + 2] = v.z; x[4 * i + 3] = v.w; }
;     ...
;     if (write_h) {
;       float ss = 0.f;
; #pragma unroll
;       for (int i = 0; i < 16; ++i) ss += x[i] * x[i];
;       ss = wave_sum(ss);
;       float rstd = rsqrtf(ss * (1.f / DM) + EPS);
;       const float* sh = modvec(p, l_mod, s, shift_idx); const float* sc = modvec(p, l_mod, s, scale_idx);
; #pragma unroll
;       for (int i = 0; i < 4; ++i) {
;         int k = i * 256 + lane * 4;
;         F4 g = *(const F4*)(g_pre + k); F4 a = *(const F4*)(sh + k); F4 c = *(const F4*)(sc + k);
;         float h0 = x[4 * i] * rstd * g.x * (1.f + c.x) + a.x, h1 = x[4 * i + 1] * rstd * g.y * (1.f + c.y) + a.y;
;         float h2 = x[4 * i + 2] * rstd * g.z * (1.f + c.z) + a.z, h3 = x[4 * i + 3] * rstd * g.w * (1.f + c.w) + a.w;
;         *(U2*)(H + (size_t)r * DM + k) = mku2(pack2(h0, h1), pack2(h2, h3));
;       }
;     }
.Lrw2_loop:
	v_mov_b32_e32 v10, v26
	v_mov_b32_e32 v11, v27
	v_mov_b32_e32 v12, v28
	v_mov_b32_e32 v13, v29
	v_mov_b32_e32 v14, v30
	v_mov_b32_e32 v15, v31
	v_mov_b32_e32 v16, v32
	v_mov_b32_e32 v17, v33
	v_mov_b32_e32 v18, v34
	v_mov_b32_e32 v19, v35
	v_mov_b32_e32 v20, v36
	v_mov_b32_e32 v21, v37
	v_mov_b32_e32 v22, v38
	v_mov_b32_e32 v23, v39
	v_mov_b32_e32 v24, v40
	v_mov_b32_e32 v25, v41
	s_mov_b32 s4, s5
	s_mul_i32 s7, s4, 0x6000
	v_mov_b32_e32 v42, s7
	v_lshl_add_u64 v[222:223], v[176:177], 0, v[42:43]
	v_lshl_add_u64 v[224:225], v[178:179], 0, v[42:43]
	s_lshl_b32 s7, s0, 11
	v_mov_b32_e32 v42, s7
	v_lshl_add_u64 v[218:219], v[182:183], 0, v[42:43]
	global_load_dwordx4 v[118:121], v[172:173], off
	global_load_dwordx4 v[122:125], v[172:173], off offset:1024
	global_load_dwordx4 v[126:129], v[172:173], off offset:2048
	global_load_dwordx4 v[130:133], v[172:173], off offset:3072
	global_load_dwordx4 v[134:137], v[222:223], off
	global_load_dwordx4 v[138:141], v[222:223], off offset:1024
	global_load_dwordx4 v[142:145], v[222:223], off offset:2048
	global_load_dwordx4 v[146:149], v[222:223], off offset:3072
	global_load_dwordx4 v[150:153], v[224:225], off
	global_load_dwordx4 v[154:157], v[224:225], off offset:1024
	global_load_dwordx4 v[158:161], v[224:225], off offset:2048
	global_load_dwordx4 v[166:169], v[224:225], off offset:3072
	s_add_i32 s1, s0, s90
	s_mov_b32 s8, 0
	s_cmp_ge_u32 s1, 0x8400
	s_cselect_b32 s8, 1, 0
	s_cselect_b32 s1, s0, s1
	s_cmp_ge_u32 s1, 0x2100
	s_cselect_b32 s2, 1, 0
	s_cmp_ge_u32 s1, 0x4200
	s_addc_u32 s2, s2, 0
	s_cmp_ge_u32 s1, 0x6300
	s_addc_u32 s2, s2, 0
	s_mul_i32 s3, s2, 0x2100
	s_sub_i32 s3, s1, s3
	s_lshl_b32 s7, s2, 8
	s_add_i32 s7, s7, s3
	s_lshl_b32 s9, s2, 13
	s_add_i32 s9, s9, s3
	s_add_i32 s9, s9, 0xffffff00
	s_cmp_lt_u32 s3, 0x100
	s_cselect_b32 s7, s7, s9
	s_cselect_b32 s5, 4, s2
	s_cselect_b64 s[12:13], -1, 0
	s_lshl_b32 s7, s7, 12
	v_add_u32_e32 v42, s7, v2
	v_cndmask_b32_e64 v190, v234, v236, s[12:13]
	v_cndmask_b32_e64 v191, v235, v237, s[12:13]
	v_lshl_add_u64 v[190:191], v[190:191], 0, v[42:43]
	global_load_dwordx4 v[26:29], v[190:191], off
	global_load_dwordx4 v[30:33], v[190:191], off offset:1024
	global_load_dwordx4 v[34:37], v[190:191], off offset:2048
	global_load_dwordx4 v[38:41], v[190:191], off offset:3072
	v_mul_f32_e32 v226, v11, v11
	v_fmac_f32_e32 v226, v10, v10
	v_fmac_f32_e32 v226, v12, v12
	v_fmac_f32_e32 v226, v13, v13
	v_fmac_f32_e32 v226, v14, v14
	v_fmac_f32_e32 v226, v15, v15
	v_fmac_f32_e32 v226, v16, v16
	v_fmac_f32_e32 v226, v17, v17
	v_fmac_f32_e32 v226, v18, v18
	v_fmac_f32_e32 v226, v19, v19
	v_fmac_f32_e32 v226, v20, v20
	v_fmac_f32_e32 v226, v21, v21
	v_mul_f32_e32 v227, v22, v22
	v_add_f32_e32 v226, v227, v226
	v_mul_f32_e32 v227, v23, v23
	v_add_f32_e32 v226, v227, v226
	v_mul_f32_e32 v227, v24, v24
	v_add_f32_e32 v226, v227, v226
	v_mul_f32_e32 v227, v25, v25
	v_add_f32_e32 v226, v227, v226
	ds_bpermute_b32 v227, v4, v226
	s_waitcnt lgkmcnt(0)
	v_add_f32_e32 v226, v226, v227
	ds_bpermute_b32 v227, v5, v226
	s_waitcnt lgkmcnt(0)
	v_add_f32_e32 v226, v226, v227
	s_nop 1
	v_add_f32_dpp v226, v226, v226 row_ror:8 row_mask:0xf bank_mask:0xf
	ds_bpermute_b32 v227, v7, v226
	s_waitcnt lgkmcnt(0)
	v_add_f32_e32 v226, v226, v227
	s_nop 1
	v_add_f32_dpp v226, v226, v226 quad_perm:[2,3,0,1] row_mask:0xf bank_mask:0xf
	s_nop 1
	v_add_f32_dpp v226, v226, v226 quad_perm:[1,0,3,2] row_mask:0xf bank_mask:0xf
	v_fmamk_f32 v226, v226, 0x3a800000, v162
	s_mov_b32 s7, 0x800000
	v_cmp_gt_f32_e32 vcc, s7, v226
	v_mul_f32_e32 v227, 0x4b800000, v226
	s_nop 0
	v_cndmask_b32_e32 v226, v226, v227, vcc
	v_rsq_f32_e32 v226, v226
	s_nop 0
	v_mul_f32_e32 v227, 0x45800000, v226
	v_cndmask_b32_e32 v228, v226, v227, vcc
	s_waitcnt vmcnt(4)
	v_pk_mul_f32 v[10:11], v[10:11], v[228:229] op_sel_hi:[1,0]
	v_pk_mul_f32 v[10:11], v[118:119], v[10:11]
	v_pk_add_f32 v[44:45], v[150:151], 1.0 op_sel_hi:[1,0]
	s_nop 0
	v_pk_fma_f32 v[10:11], v[44:45], v[10:11], v[134:135]
	v_pk_mul_f32 v[12:13], v[12:13], v[228:229] op_sel_hi:[1,0]
	v_pk_mul_f32 v[12:13], v[120:121], v[12:13]
	v_pk_add_f32 v[46:47], v[152:153], 1.0 op_sel_hi:[1,0]
	s_nop 0
	v_pk_fma_f32 v[12:13], v[46:47], v[12:13], v[136:137]
	v_cvt_pk_bf16_f32 v48, v10, v11
	v_cvt_pk_bf16_f32 v49, v12, v13
	global_store_dwordx2 v[218:219], v[48:49], off
	s_nop 1
	v_pk_mul_f32 v[14:15], v[14:15], v[228:229] op_sel_hi:[1,0]
	v_pk_mul_f32 v[14:15], v[122:123], v[14:15]
	v_pk_add_f32 v[44:45], v[154:155], 1.0 op_sel_hi:[1,0]
	s_nop 0
	v_pk_fma_f32 v[14:15], v[44:45], v[14:15], v[138:139]
	v_pk_mul_f32 v[16:17], v[16:17], v[228:229] op_sel_hi:[1,0]
	v_pk_mul_f32 v[16:17], v[124:125], v[16:17]
	v_pk_add_f32 v[46:47], v[156:157], 1.0 op_sel_hi:[1,0]
	s_nop 0
	v_pk_fma_f32 v[16:17], v[46:47], v[16:17], v[140:141]
	v_cvt_pk_bf16_f32 v48, v14, v15
	v_cvt_pk_bf16_f32 v49, v16, v17
	global_store_dwordx2 v[218:219], v[48:49], off offset:512
	s_nop 1
	v_pk_mul_f32 v[18:19], v[18:19], v[228:229] op_sel_hi:[1,0]
	v_pk_mul_f32 v[18:19], v[126:127], v[18:19]
	v_pk_add_f32 v[44:45], v[158:159], 1.0 op_sel_hi:[1,0]
	s_nop 0
	v_pk_fma_f32 v[18:19], v[44:45], v[18:19], v[142:143]
	v_pk_mul_f32 v[20:21], v[20:21], v[228:229] op_sel_hi:[1,0]
	v_pk_mul_f32 v[20:21], v[128:129], v[20:21]
	v_pk_add_f32 v[46:47], v[160:161], 1.0 op_sel_hi:[1,0]
	s_nop 0
	v_pk_fma_f32 v[20:21], v[46:47], v[20:21], v[144:145]
	v_cvt_pk_bf16_f32 v48, v18, v19
	v_cvt_pk_bf16_f32 v49, v20, v21
	global_store_dwordx2 v[218:219], v[48:49], off offset:1024
	s_nop 1
	v_pk_mul_f32 v[22:23], v[22:23], v[228:229] op_sel_hi:[1,0]
	v_pk_mul_f32 v[22:23], v[130:131], v[22:23]
	v_pk_add_f32 v[44:45], v[166:167], 1.0 op_sel_hi:[1,0]
	s_nop 0
	v_pk_fma_f32 v[22:23], v[44:45], v[22:23], v[146:147]
	v_pk_mul_f32 v[24:25], v[24:25], v[228:229] op_sel_hi:[1,0]
	v_pk_mul_f32 v[24:25], v[132:133], v[24:25]
	v_pk_add_f32 v[46:47], v[168:169], 1.0 op_sel_hi:[1,0]
	s_nop 0
	v_pk_fma_f32 v[24:25], v[46:47], v[24:25], v[148:149]
	v_cvt_pk_bf16_f32 v48, v22, v23
	v_cvt_pk_bf16_f32 v49, v24, v25
	global_store_dwordx2 v[218:219], v[48:49], off offset:1536
	s_nop 1
	s_waitcnt vmcnt(4)
	s_cmp_eq_u32 s8, 1
	s_cbranch_scc1 .Lrw2_done
	s_mov_b32 s0, s1
	s_branch .Lrw2_loop
